# P10: per-tile vmcnt(0) at the tile top moved to the prologue; first two waits of the peeled iteration removed so the second tile's first K-iteration overlaps the first tile's store drain
# baseline (speedup 1.0000x reference)
.LBB0_1330:
	s_add_u32 s6, s22, 0x1c00000
	v_readlane_b32 s48, v246, 0
	s_addc_u32 s7, s23, 0
	s_add_i32 s26, s48, 0x18000
	s_and_b32 s15, s8, 3
	s_add_i32 s41, s26, s12
	s_mov_b64 s[8:9], 0x80
	s_lshl_b32 s24, s11, 13
	s_lshl_b32 s25, s15, 12
	v_lshl_add_u64 v[6:7], v[6:7], 0, s[8:9]
	s_mov_b32 m0, s41
	s_add_i32 s42, s41, 0x2000
	s_add_i32 s43, s35, 0x8000
	s_add_i32 s44, s35, 0xa000
	global_load_lds_dwordx4 v[6:7], off
	v_lshl_add_u64 v[4:5], v[4:5], 0, s[8:9]
	s_mov_b32 m0, s42
	s_add_u32 s22, s18, 0xb0080
	global_load_lds_dwordx4 v[4:5], off
	v_lshl_add_u64 v[2:3], v[2:3], 0, s[8:9]
	s_mov_b32 m0, s43
	s_addc_u32 s23, s19, 0
	s_add_i32 s27, s48, 0x1c000
	global_load_lds_dwordx4 v[2:3], off
	v_lshl_add_u64 v[0:1], v[0:1], 0, s[8:9]
	s_mov_b32 m0, s44
	s_add_i32 s45, s27, s12
	global_load_lds_dwordx4 v[0:1], off
	v_lshl_add_u64 v[0:1], s[22:23], 0, v[138:139]
	s_mov_b32 m0, s45
	s_add_i32 s46, s45, 0x2000
	global_load_lds_dwordx4 v[0:1], off
	v_lshl_add_u64 v[0:1], s[22:23], 0, v[136:137]
	s_mov_b32 m0, s46
	s_sext_i32_i8 s51, s10
	global_load_lds_dwordx4 v[0:1], off
	s_waitcnt vmcnt(8)
	s_barrier
	v_lshrrev_b32_e32 v1, 1, v202
	v_and_b32_e32 v1, 24, v1
	v_and_b32_e32 v0, 15, v202
	v_lshlrev_b32_e32 v2, 1, v1
	v_lshlrev_b32_e32 v3, 2, v202
	v_lshlrev_b32_e32 v4, 6, v202
	s_movk_i32 s10, 0x3c0
	v_lshl_or_b32 v160, s11, 6, v0
	v_lshl_or_b32 v0, v0, 6, v2
	v_and_b32_e32 v3, 32, v3
	v_and_or_b32 v2, v4, s10, v2
	s_waitcnt vmcnt(6)
	v_bitop3_b32 v0, v0, s24, v3 bitop3:0xde
	v_bitop3_b32 v2, s25, v2, v3 bitop3:0xf6
	v_readlane_b32 s10, v246, 1
	v_readlane_b32 s11, v246, 2
	s_ashr_i32 s47, s10, 31
	v_lshl_or_b32 v161, s15, 6, v1
	v_add3_u32 v140, v11, v9, v10
	v_mov_b32_e32 v141, v139
	v_add3_u32 v142, v8, v9, v10
	v_mov_b32_e32 v143, v139
	v_mov_b64_e32 v[144:145], s[0:1]
	v_add_u32_e32 v162, s13, v2
	v_add_u32_e32 v163, s48, v0
	v_add_u32_e32 v164, s14, v2
	v_add_u32_e32 v165, s26, v2
	v_add_u32_e32 v166, s27, v2
	s_barrier
	s_waitcnt vmcnt(0)

.LBB0_1335:
	s_xor_b64 s[14:15], s[22:23], -1
	s_and_b64 s[22:23], s[22:23], exec
	s_cselect_b32 s24, s11, s17
	s_cselect_b32 s25, s10, s16
	s_cselect_b32 s26, s13, s19
	s_cselect_b32 s27, s12, s18
	s_add_u32 s16, s16, 0xb0080
	s_addc_u32 s17, s17, 0
	s_add_u32 s52, s18, 0x100
	s_addc_u32 s53, s19, 0
	s_mov_b32 s54, -2
	s_nop 0
	ds_read_b128 v[128:131], v162
	ds_read_b128 v[132:135], v162 offset:1024
	ds_read_b128 v[146:149], v162 offset:2048
	ds_read_b128 v[150:153], v162 offset:3072
	s_add_u32 s18, s16, 0xfff50080
	s_addc_u32 s19, s17, -1
	s_cmp_eq_u32 s54, 40
	s_cselect_b32 s23, s24, s19
	s_cselect_b32 s22, s25, s18
	s_cselect_b32 s19, s26, s53
	s_cselect_b32 s18, s27, s52
	v_lshl_add_u64 v[158:159], s[16:17], 0, v[140:141]
	s_add_i32 m0, s35, 0xc000
	ds_read_b128 v[154:157], v163
	ds_read_b128 v[168:171], v163 offset:1024
	ds_read_b128 v[172:175], v163 offset:2048
	ds_read_b128 v[176:179], v163 offset:3072
	ds_read_b128 v[180:183], v163 offset:4096
	ds_read_b128 v[184:187], v163 offset:5120
	ds_read_b128 v[188:191], v163 offset:6144
	ds_read_b128 v[192:195], v163 offset:7168
	global_load_lds_dwordx4 v[158:159], off
	v_lshl_add_u64 v[158:159], s[16:17], 0, v[142:143]
	s_add_i32 m0, s35, 0xe000
	s_nop 0
	global_load_lds_dwordx4 v[158:159], off
	ds_read_b128 v[196:199], v164
	ds_read_b128 v[200:203], v164 offset:1024
	ds_read_b128 v[204:207], v164 offset:2048
	ds_read_b128 v[208:211], v164 offset:3072
	s_waitcnt lgkmcnt(0)
	s_nop 0
	s_barrier
	s_setprio 1
	v_mfma_f32_16x16x32_bf16 v[124:127], v[128:131], v[154:157], 0
	v_mfma_f32_16x16x32_bf16 v[120:123], v[146:149], v[154:157], 0
	v_mfma_f32_16x16x32_bf16 v[116:119], v[128:131], v[172:175], 0
	v_mfma_f32_16x16x32_bf16 v[112:115], v[146:149], v[172:175], 0
	v_mfma_f32_16x16x32_bf16 v[92:95], v[128:131], v[180:183], 0
	v_mfma_f32_16x16x32_bf16 v[88:91], v[146:149], v[180:183], 0
	v_mfma_f32_16x16x32_bf16 v[76:79], v[128:131], v[188:191], 0
	v_mfma_f32_16x16x32_bf16 v[72:75], v[146:149], v[188:191], 0
	v_mfma_f32_16x16x32_bf16 v[124:127], v[132:135], v[168:171], v[124:127]
	v_mfma_f32_16x16x32_bf16 v[120:123], v[150:153], v[168:171], v[120:123]
	v_mfma_f32_16x16x32_bf16 v[116:119], v[132:135], v[176:179], v[116:119]
	v_mfma_f32_16x16x32_bf16 v[112:115], v[150:153], v[176:179], v[112:115]
	v_mfma_f32_16x16x32_bf16 v[92:95], v[132:135], v[184:187], v[92:95]
	v_mfma_f32_16x16x32_bf16 v[88:91], v[150:153], v[184:187], v[88:91]
	v_mfma_f32_16x16x32_bf16 v[76:79], v[132:135], v[192:195], v[76:79]
	v_mfma_f32_16x16x32_bf16 v[72:75], v[150:153], v[192:195], v[72:75]
	v_mfma_f32_16x16x32_bf16 v[108:111], v[196:199], v[154:157], 0
	v_mfma_f32_16x16x32_bf16 v[104:107], v[204:207], v[154:157], 0
	v_mfma_f32_16x16x32_bf16 v[100:103], v[196:199], v[172:175], 0
	v_mfma_f32_16x16x32_bf16 v[96:99], v[204:207], v[172:175], 0
	v_mfma_f32_16x16x32_bf16 v[84:87], v[196:199], v[180:183], 0
	v_mfma_f32_16x16x32_bf16 v[80:83], v[204:207], v[180:183], 0
	v_mfma_f32_16x16x32_bf16 v[68:71], v[196:199], v[188:191], 0
	v_mfma_f32_16x16x32_bf16 v[64:67], v[204:207], v[188:191], 0
	v_mfma_f32_16x16x32_bf16 v[108:111], v[200:203], v[168:171], v[108:111]
	v_mfma_f32_16x16x32_bf16 v[104:107], v[208:211], v[168:171], v[104:107]
	v_mfma_f32_16x16x32_bf16 v[100:103], v[200:203], v[176:179], v[100:103]
	v_mfma_f32_16x16x32_bf16 v[96:99], v[208:211], v[176:179], v[96:99]
	v_mfma_f32_16x16x32_bf16 v[84:87], v[200:203], v[184:187], v[84:87]
	v_mfma_f32_16x16x32_bf16 v[80:83], v[208:211], v[184:187], v[80:83]
	v_mfma_f32_16x16x32_bf16 v[68:71], v[200:203], v[192:195], v[68:71]
	v_mfma_f32_16x16x32_bf16 v[64:67], v[208:211], v[192:195], v[64:67]
	s_setprio 0
	s_barrier
	ds_read_b128 v[154:157], v163 offset:16384
	ds_read_b128 v[168:171], v163 offset:17408
	ds_read_b128 v[172:175], v163 offset:18432
	ds_read_b128 v[176:179], v163 offset:19456
	ds_read_b128 v[180:183], v163 offset:20480
	ds_read_b128 v[184:187], v163 offset:21504
	ds_read_b128 v[188:191], v163 offset:22528
	ds_read_b128 v[192:195], v163 offset:23552
	s_mov_b32 m0, s33
	v_lshl_add_u64 v[158:159], s[18:19], 0, v[138:139]
	global_load_lds_dwordx4 v[158:159], off
	v_lshl_add_u64 v[212:213], s[18:19], 0, v[136:137]
	s_mov_b32 m0, s34
	s_nop 0
	global_load_lds_dwordx4 v[212:213], off
	s_mov_b32 m0, s35
	v_lshl_add_u64 v[214:215], s[22:23], 0, v[138:139]
	global_load_lds_dwordx4 v[214:215], off
	v_lshl_add_u64 v[216:217], s[22:23], 0, v[136:137]
	s_mov_b32 m0, s36
	s_nop 0
	global_load_lds_dwordx4 v[216:217], off
	s_add_u32 s56, s18, 0xb0000
	s_addc_u32 s57, s19, 0
	s_mov_b32 m0, s37
	v_lshl_add_u64 v[248:249], s[56:57], 0, v[138:139]
	global_load_lds_dwordx4 v[248:249], off
	v_lshl_add_u64 v[248:249], s[56:57], 0, v[136:137]
	s_mov_b32 m0, s38
	s_nop 0
	global_load_lds_dwordx4 v[248:249], off
	s_waitcnt lgkmcnt(0)
	s_nop 0
	s_barrier
	s_setprio 1
	v_mfma_f32_16x16x32_bf16 v[60:63], v[128:131], v[154:157], 0
	v_mfma_f32_16x16x32_bf16 v[56:59], v[146:149], v[154:157], 0
	v_mfma_f32_16x16x32_bf16 v[44:47], v[128:131], v[172:175], 0
	v_mfma_f32_16x16x32_bf16 v[40:43], v[146:149], v[172:175], 0
	v_mfma_f32_16x16x32_bf16 v[28:31], v[128:131], v[180:183], 0
	v_mfma_f32_16x16x32_bf16 v[24:27], v[146:149], v[180:183], 0
	v_mfma_f32_16x16x32_bf16 v[12:15], v[128:131], v[188:191], 0
	v_mfma_f32_16x16x32_bf16 v[8:11], v[146:149], v[188:191], 0
	v_mfma_f32_16x16x32_bf16 v[60:63], v[132:135], v[168:171], v[60:63]
	v_mfma_f32_16x16x32_bf16 v[56:59], v[150:153], v[168:171], v[56:59]
	v_mfma_f32_16x16x32_bf16 v[44:47], v[132:135], v[176:179], v[44:47]
	v_mfma_f32_16x16x32_bf16 v[40:43], v[150:153], v[176:179], v[40:43]
	v_mfma_f32_16x16x32_bf16 v[28:31], v[132:135], v[184:187], v[28:31]
	v_mfma_f32_16x16x32_bf16 v[24:27], v[150:153], v[184:187], v[24:27]
	v_mfma_f32_16x16x32_bf16 v[12:15], v[132:135], v[192:195], v[12:15]
	v_mfma_f32_16x16x32_bf16 v[8:11], v[150:153], v[192:195], v[8:11]
	v_mfma_f32_16x16x32_bf16 v[52:55], v[196:199], v[154:157], 0
	v_mfma_f32_16x16x32_bf16 v[48:51], v[204:207], v[154:157], 0
	v_mfma_f32_16x16x32_bf16 v[36:39], v[196:199], v[172:175], 0
	v_mfma_f32_16x16x32_bf16 v[32:35], v[204:207], v[172:175], 0
	v_mfma_f32_16x16x32_bf16 v[20:23], v[196:199], v[180:183], 0
	v_mfma_f32_16x16x32_bf16 v[16:19], v[204:207], v[180:183], 0
	v_mfma_f32_16x16x32_bf16 v[4:7], v[196:199], v[188:191], 0
	v_mfma_f32_16x16x32_bf16 v[0:3], v[204:207], v[188:191], 0
	v_mfma_f32_16x16x32_bf16 v[52:55], v[200:203], v[168:171], v[52:55]
	v_mfma_f32_16x16x32_bf16 v[48:51], v[208:211], v[168:171], v[48:51]
	v_mfma_f32_16x16x32_bf16 v[36:39], v[200:203], v[176:179], v[36:39]
	v_mfma_f32_16x16x32_bf16 v[32:35], v[208:211], v[176:179], v[32:35]
	v_mfma_f32_16x16x32_bf16 v[20:23], v[200:203], v[184:187], v[20:23]
	v_mfma_f32_16x16x32_bf16 v[16:19], v[208:211], v[184:187], v[16:19]
	v_mfma_f32_16x16x32_bf16 v[4:7], v[200:203], v[192:195], v[4:7]
	v_mfma_f32_16x16x32_bf16 v[0:3], v[208:211], v[192:195], v[0:3]
	s_setprio 0
	s_barrier
	ds_read_b128 v[128:131], v165
	ds_read_b128 v[132:135], v165 offset:1024
	ds_read_b128 v[146:149], v165 offset:2048
	ds_read_b128 v[150:153], v165 offset:3072
	s_add_u32 s22, s22, 0xb0000
	s_addc_u32 s23, s23, 0
	s_mov_b32 m0, s39
	v_lshl_add_u64 v[196:197], s[22:23], 0, v[138:139]
	ds_read_b128 v[154:157], v163 offset:32768
	ds_read_b128 v[168:171], v163 offset:33792
	ds_read_b128 v[172:175], v163 offset:34816
	ds_read_b128 v[176:179], v163 offset:35840
	ds_read_b128 v[180:183], v163 offset:36864
	ds_read_b128 v[184:187], v163 offset:37888
	ds_read_b128 v[188:191], v163 offset:38912
	ds_read_b128 v[192:195], v163 offset:39936
	global_load_lds_dwordx4 v[196:197], off
	v_lshl_add_u64 v[196:197], s[22:23], 0, v[136:137]
	s_mov_b32 m0, s40
	s_nop 0
	global_load_lds_dwordx4 v[196:197], off
	ds_read_b128 v[196:199], v166
	ds_read_b128 v[200:203], v166 offset:1024
	ds_read_b128 v[204:207], v166 offset:2048
	ds_read_b128 v[208:211], v166 offset:3072
	s_waitcnt lgkmcnt(0)
	s_waitcnt vmcnt(8)
	s_barrier
	s_setprio 1
	v_mfma_f32_16x16x32_bf16 v[124:127], v[128:131], v[154:157], v[124:127]
	v_mfma_f32_16x16x32_bf16 v[120:123], v[146:149], v[154:157], v[120:123]
	v_mfma_f32_16x16x32_bf16 v[116:119], v[128:131], v[172:175], v[116:119]
	v_mfma_f32_16x16x32_bf16 v[112:115], v[146:149], v[172:175], v[112:115]
	v_mfma_f32_16x16x32_bf16 v[92:95], v[128:131], v[180:183], v[92:95]
	v_mfma_f32_16x16x32_bf16 v[88:91], v[146:149], v[180:183], v[88:91]
	v_mfma_f32_16x16x32_bf16 v[76:79], v[128:131], v[188:191], v[76:79]
	v_mfma_f32_16x16x32_bf16 v[72:75], v[146:149], v[188:191], v[72:75]
	v_mfma_f32_16x16x32_bf16 v[124:127], v[132:135], v[168:171], v[124:127]
	v_mfma_f32_16x16x32_bf16 v[120:123], v[150:153], v[168:171], v[120:123]
	v_mfma_f32_16x16x32_bf16 v[116:119], v[132:135], v[176:179], v[116:119]
	v_mfma_f32_16x16x32_bf16 v[112:115], v[150:153], v[176:179], v[112:115]
	v_mfma_f32_16x16x32_bf16 v[92:95], v[132:135], v[184:187], v[92:95]
	v_mfma_f32_16x16x32_bf16 v[88:91], v[150:153], v[184:187], v[88:91]
	v_mfma_f32_16x16x32_bf16 v[76:79], v[132:135], v[192:195], v[76:79]
	v_mfma_f32_16x16x32_bf16 v[72:75], v[150:153], v[192:195], v[72:75]
	v_mfma_f32_16x16x32_bf16 v[108:111], v[196:199], v[154:157], v[108:111]
	v_mfma_f32_16x16x32_bf16 v[104:107], v[204:207], v[154:157], v[104:107]
	v_mfma_f32_16x16x32_bf16 v[100:103], v[196:199], v[172:175], v[100:103]
	v_mfma_f32_16x16x32_bf16 v[96:99], v[204:207], v[172:175], v[96:99]
	v_mfma_f32_16x16x32_bf16 v[84:87], v[196:199], v[180:183], v[84:87]
	v_mfma_f32_16x16x32_bf16 v[80:83], v[204:207], v[180:183], v[80:83]
	v_mfma_f32_16x16x32_bf16 v[68:71], v[196:199], v[188:191], v[68:71]
	v_mfma_f32_16x16x32_bf16 v[64:67], v[204:207], v[188:191], v[64:67]
	v_mfma_f32_16x16x32_bf16 v[108:111], v[200:203], v[168:171], v[108:111]
	v_mfma_f32_16x16x32_bf16 v[104:107], v[208:211], v[168:171], v[104:107]
	v_mfma_f32_16x16x32_bf16 v[100:103], v[200:203], v[176:179], v[100:103]
	v_mfma_f32_16x16x32_bf16 v[96:99], v[208:211], v[176:179], v[96:99]
	v_mfma_f32_16x16x32_bf16 v[84:87], v[200:203], v[184:187], v[84:87]
	v_mfma_f32_16x16x32_bf16 v[80:83], v[208:211], v[184:187], v[80:83]
	v_mfma_f32_16x16x32_bf16 v[68:71], v[200:203], v[192:195], v[68:71]
	v_mfma_f32_16x16x32_bf16 v[64:67], v[208:211], v[192:195], v[64:67]
	s_setprio 0
	s_barrier
	ds_read_b128 v[154:157], v163 offset:49152
	ds_read_b128 v[168:171], v163 offset:50176
	ds_read_b128 v[172:175], v163 offset:51200
	ds_read_b128 v[176:179], v163 offset:52224
	ds_read_b128 v[180:183], v163 offset:53248
	ds_read_b128 v[184:187], v163 offset:54272
	ds_read_b128 v[188:191], v163 offset:55296
	ds_read_b128 v[192:195], v163 offset:56320
	s_mov_b32 m0, s41
	v_lshl_add_u64 v[158:159], v[158:159], 0, s[8:9]
	global_load_lds_dwordx4 v[158:159], off
	v_lshl_add_u64 v[158:159], v[212:213], 0, s[8:9]
	s_mov_b32 m0, s42
	s_nop 0
	global_load_lds_dwordx4 v[158:159], off
	s_mov_b32 m0, s43
	v_lshl_add_u64 v[158:159], v[214:215], 0, s[8:9]
	global_load_lds_dwordx4 v[158:159], off
	v_lshl_add_u64 v[158:159], v[216:217], 0, s[8:9]
	s_mov_b32 m0, s44
	s_nop 0
	global_load_lds_dwordx4 v[158:159], off
	s_add_u32 s18, s18, 0xb0080
	s_addc_u32 s19, s19, 0
	s_mov_b32 m0, s45
	v_lshl_add_u64 v[248:249], s[18:19], 0, v[138:139]
	global_load_lds_dwordx4 v[248:249], off
	v_lshl_add_u64 v[248:249], s[18:19], 0, v[136:137]
	s_mov_b32 m0, s46
	s_nop 0
	global_load_lds_dwordx4 v[248:249], off
	s_waitcnt lgkmcnt(0)
	s_waitcnt vmcnt(8)
	s_barrier
	s_setprio 1
	v_mfma_f32_16x16x32_bf16 v[60:63], v[128:131], v[154:157], v[60:63]
	v_mfma_f32_16x16x32_bf16 v[56:59], v[146:149], v[154:157], v[56:59]
	v_mfma_f32_16x16x32_bf16 v[44:47], v[128:131], v[172:175], v[44:47]
	v_mfma_f32_16x16x32_bf16 v[40:43], v[146:149], v[172:175], v[40:43]
	v_mfma_f32_16x16x32_bf16 v[28:31], v[128:131], v[180:183], v[28:31]
	v_mfma_f32_16x16x32_bf16 v[24:27], v[146:149], v[180:183], v[24:27]
	v_mfma_f32_16x16x32_bf16 v[12:15], v[128:131], v[188:191], v[12:15]
	v_mfma_f32_16x16x32_bf16 v[8:11], v[146:149], v[188:191], v[8:11]
	v_mfma_f32_16x16x32_bf16 v[60:63], v[132:135], v[168:171], v[60:63]
	v_mfma_f32_16x16x32_bf16 v[56:59], v[150:153], v[168:171], v[56:59]
	v_mfma_f32_16x16x32_bf16 v[44:47], v[132:135], v[176:179], v[44:47]
	v_mfma_f32_16x16x32_bf16 v[40:43], v[150:153], v[176:179], v[40:43]
	v_mfma_f32_16x16x32_bf16 v[28:31], v[132:135], v[184:187], v[28:31]
	v_mfma_f32_16x16x32_bf16 v[24:27], v[150:153], v[184:187], v[24:27]
	v_mfma_f32_16x16x32_bf16 v[12:15], v[132:135], v[192:195], v[12:15]
	v_mfma_f32_16x16x32_bf16 v[8:11], v[150:153], v[192:195], v[8:11]
	v_mfma_f32_16x16x32_bf16 v[52:55], v[196:199], v[154:157], v[52:55]
	v_mfma_f32_16x16x32_bf16 v[48:51], v[204:207], v[154:157], v[48:51]
	v_mfma_f32_16x16x32_bf16 v[36:39], v[196:199], v[172:175], v[36:39]
	v_mfma_f32_16x16x32_bf16 v[32:35], v[204:207], v[172:175], v[32:35]
	v_mfma_f32_16x16x32_bf16 v[20:23], v[196:199], v[180:183], v[20:23]
	v_mfma_f32_16x16x32_bf16 v[16:19], v[204:207], v[180:183], v[16:19]
	v_mfma_f32_16x16x32_bf16 v[4:7], v[196:199], v[188:191], v[4:7]
	v_mfma_f32_16x16x32_bf16 v[0:3], v[204:207], v[188:191], v[0:3]
	v_mfma_f32_16x16x32_bf16 v[52:55], v[200:203], v[168:171], v[52:55]
	v_mfma_f32_16x16x32_bf16 v[48:51], v[208:211], v[168:171], v[48:51]
	v_mfma_f32_16x16x32_bf16 v[36:39], v[200:203], v[176:179], v[36:39]
	v_mfma_f32_16x16x32_bf16 v[32:35], v[208:211], v[176:179], v[32:35]
	v_mfma_f32_16x16x32_bf16 v[20:23], v[200:203], v[184:187], v[20:23]
	v_mfma_f32_16x16x32_bf16 v[16:19], v[208:211], v[184:187], v[16:19]
	v_mfma_f32_16x16x32_bf16 v[4:7], v[200:203], v[192:195], v[4:7]
	v_mfma_f32_16x16x32_bf16 v[0:3], v[208:211], v[192:195], v[0:3]
	s_setprio 0
	s_add_i32 s54, s54, 2
	s_add_u32 s16, s16, 0x100
	s_addc_u32 s17, s17, 0
	s_add_u32 s52, s52, 0x100
	s_addc_u32 s53, s53, 0
	s_cmp_gt_u32 s54, 41
	s_barrier
